# gdn_prep: v row loads of the 4 conv taps also issued at the job top (direct into conv registers), beta/g stage temporaries renamed
# speedup vs baseline: 1.0134x; 1.0028x over previous
; #define GAS __attribute__((address_space(1)))
; #define LAS __attribute__((address_space(3)))
; #define LDS_WAIT() asm volatile("s_waitcnt lgkmcnt(0)" ::: "memory")
; DI float fexp(float x) { return __builtin_amdgcn_exp2f(x * 1.4426950408889634f); }
; DI float sigm(float x) { return frcp(1.f + fexp(-x)); }
; DI float softplus(float x) { return fmaxf(x, 0.f) + flog(1.f + fexp(-fabsf(x))); }
;     ...
;     if (tid < 384) { const int j = tid / 96, i96 = tid % 96, seg = i96 >> 5, c4 = (i96 & 31) * 4;
;         const f32x4 cwv = *(const GAS f32x4*)(F.in[15] + ((size_t)layer * 4 + j) * 2304 + seg * 768 + h * 128 + c4);
;         *(LAS f32x4*)(L + gp::CW + (j * 384 + seg * 128 + c4) * 4) = cwv; }
;     if (wave == 0) {
;         const float* pba = PBA + (m0 + lane) * 16;
;         const float beta = sigm(pba[h]);
;         float g = -fexp(F.in[16][layer * 6 + h]) * softplus(pba[6 + h] + F.in[17][layer * 6 + h]);
; #pragma unroll
;         for (int o = 1; o < 64; o <<= 1) { const float v = __shfl_up(g, o); if (lane >= o) g += v; }
;         const float blast = __shfl(g, 63);
;         BETA[lane] = beta; BC[lane] = g;
;         if (lane == 0) { BC[64] = blast; ((float*)(F.ws + WS_GE))[cidx] = fexp(blast); }
;     }
;     LDS_WAIT(); __syncthreads();
;     const float blast = BC[64];
;         const int t2 = tid >> 3, c02 = 16 * (tid & 7);
;         const int pcol2 = PC_V + h * 128 + c02, wch2 = 1536 + h * 128 + c02;
;         float av[16];
; #pragma unroll
;         for (int c = 0; c < 16; ++c) av[c] = 0.f;
;         v4u xv[4][2];
; #pragma unroll
;         for (int j = 0; j < 4; ++j) {
;             const int tt = t0 + t2 - 3 + j;
;             if (tt >= 0) { const bf16* src = P + ((size_t)b * SEQ + tt) * NP + pcol2; xv[j][0] = *(const GAS v4u*)src; xv[j][1] = *(const GAS v4u*)(src + 8); }
.LBB0_715:
	s_ashr_i32 s62, s47, 6
	s_mul_hi_i32 s2, s62, 0x2aaaaaab
	s_lshr_b32 s48, s2, 31
	s_add_i32 s64, s2, s48
	s_mul_i32 s2, s64, 6
	s_sub_i32 s60, s62, s2
	s_and_saveexec_b64 s[66:67], s[40:41]
	s_cbranch_execz .LBB0_717
	s_load_dwordx2 s[48:49], s[82:83], 0x78
	v_mov_b32_e32 v75, v97
	s_waitcnt lgkmcnt(0)
	v_lshl_add_u64 v[250:251], s[48:49], 0, v[64:65]
	s_lshl_b32 s48, s60, 7
	v_lshl_add_u64 v[250:251], v[66:67], 2, v[250:251]
	s_ashr_i32 s49, s48, 31
	v_lshl_add_u64 v[250:251], s[48:49], 2, v[250:251]
	v_lshl_add_u64 v[250:251], v[250:251], 0, v[74:75]
	global_load_dwordx4 v[238:241], v[250:251], off
.LBB0_717:
	s_or_b64 exec, exec, s[66:67]
	s_ashr_i32 s63, s62, 31
	s_and_b32 s48, s47, 63
	s_ashr_i32 s65, s64, 31
	s_lshl_b64 s[76:77], s[62:63], 6
	s_lshl_b32 s2, s48, 6
	s_lshl_b64 s[86:87], s[64:65], 12
	s_lshl_b32 s100, s60, 7
	v_add_u32_e32 v98, s100, v131
	v_mov_b32_e32 v99, v97
	v_lshl_add_u64 v[248:249], v[98:99], 1, s[0:1]
	v_add_u32_e32 v98, s100, v137
	v_mov_b32_e32 v99, v97
	v_add_u32_e32 v233, s2, v132
	v_lshl_add_u64 v[62:63], v[98:99], 1, s[0:1]
	v_add_u32_e32 v242, s86, v233
	v_cmp_lt_i32_e32 vcc, -1, v233
	s_and_saveexec_b64 s[100:101], vcc
	v_mad_u64_u32 v[250:251], vcc, v242, s97, v[62:63]
	v_mad_u64_u32 v[246:247], vcc, v242, s97, v[248:249]
	global_load_dwordx4 v[24:27], v[246:247], off offset:16
	global_load_dwordx4 v[28:31], v[246:247], off
	global_load_dwordx4 v[54:57], v[250:251], off offset:48
	global_load_dwordx4 v[58:61], v[250:251], off offset:32
	global_load_dwordx4 v[102:105], v[250:251], off offset:16
	global_load_dwordx4 v[106:109], v[250:251], off
	s_mov_b64 exec, s[100:101]
	v_add_u32_e32 v242, 1, v242
	v_cmp_lt_i32_e32 vcc, -2, v233
	s_and_saveexec_b64 s[100:101], vcc
	v_mad_u64_u32 v[250:251], vcc, v242, s97, v[62:63]
	v_mad_u64_u32 v[246:247], vcc, v242, s97, v[248:249]
	global_load_dwordx4 v[16:19], v[246:247], off offset:16
	global_load_dwordx4 v[20:23], v[246:247], off
	global_load_dwordx4 v[110:113], v[250:251], off offset:48
	global_load_dwordx4 v[114:117], v[250:251], off offset:32
	global_load_dwordx4 v[118:121], v[250:251], off offset:16
	global_load_dwordx4 v[122:125], v[250:251], off
	s_mov_b64 exec, s[100:101]
	v_add_u32_e32 v242, 1, v242
	v_cmp_lt_i32_e32 vcc, -3, v233
	s_and_saveexec_b64 s[100:101], vcc
	v_mad_u64_u32 v[250:251], vcc, v242, s97, v[62:63]
	v_mad_u64_u32 v[246:247], vcc, v242, s97, v[248:249]
	global_load_dwordx4 v[4:7], v[246:247], off offset:16
	global_load_dwordx4 v[12:15], v[246:247], off
	global_load_dwordx4 v[126:129], v[250:251], off offset:48
	global_load_dwordx4 v[202:205], v[250:251], off offset:32
	global_load_dwordx4 v[206:209], v[250:251], off offset:16
	global_load_dwordx4 v[210:213], v[250:251], off
	s_mov_b64 exec, s[100:101]
	v_add_u32_e32 v242, 1, v242
	v_cmp_lt_i32_e32 vcc, -4, v233
	s_and_saveexec_b64 s[100:101], vcc
	v_mad_u64_u32 v[250:251], vcc, v242, s97, v[62:63]
	v_mad_u64_u32 v[246:247], vcc, v242, s97, v[248:249]
	global_load_dwordx4 v[0:3], v[246:247], off offset:16
	global_load_dwordx4 v[8:11], v[246:247], off
	global_load_dwordx4 v[214:217], v[250:251], off offset:48
	global_load_dwordx4 v[218:221], v[250:251], off offset:32
	global_load_dwordx4 v[222:225], v[250:251], off offset:16
	global_load_dwordx4 v[234:237], v[250:251], off
	s_mov_b64 exec, s[100:101]
	s_andn2_b64 vcc, exec, s[80:81]
	s_or_b32 s76, s76, s48
	s_cbranch_vccnz .LBB0_721
	s_load_dwordx4 s[64:67], s[82:83], 0x80
	v_readlane_b32 s48, v255, 17
	s_mul_i32 s48, s48, 6
	s_add_i32 s48, s60, s48
	s_ashr_i32 s49, s48, 31
	v_or_b32_e32 v62, s2, v71
	s_ashr_i32 s61, s60, 31
	s_lshl_b64 s[48:49], s[48:49], 2
	v_or_b32_e32 v62, s86, v62
	v_mov_b32_e32 v63, s87
	s_waitcnt lgkmcnt(0)
	s_add_u32 s62, s64, s48
	v_lshlrev_b64 v[62:63], 6, v[62:63]
	s_addc_u32 s63, s65, s49
	v_lshl_add_u64 v[62:63], s[78:79], 0, v[62:63]
	s_add_u32 s48, s66, s48
	v_lshl_add_u64 v[62:63], s[60:61], 2, v[62:63]
	s_addc_u32 s49, s67, s49
	flat_load_dword v98, v[62:63]
	global_load_dword v99, v97, s[62:63]
	v_and_b32_e32 v233, 64, v228
	flat_load_dword v62, v[62:63] offset:24
	v_add_u32_e32 v242, -1, v228
	global_load_dword v63, v97, s[48:49]
	s_mov_b32 s48, 0xbfb8aa3b
	v_cmp_lt_i32_e32 vcc, v242, v233
	s_waitcnt vmcnt(0) lgkmcnt(0)
	v_mul_f32_e32 v98, 0xbfb8aa3b, v98
	v_mul_f32_e32 v99, 0x3fb8aa3b, v99
	v_exp_f32_e32 v99, v99
	v_cndmask_b32_e32 v242, v242, v228, vcc
	v_lshlrev_b32_e32 v242, 2, v242
	v_add_f32_e32 v62, v62, v63
	v_max_f32_e32 v63, 0, v62
	v_mul_f32_e64 v62, |v62|, s48
	v_exp_f32_e32 v62, v62
	v_readlane_b32 s48, v255, 21
	v_readlane_b32 s49, v255, 22
	v_exp_f32_e32 v98, v98
	v_add_f32_e32 v62, 1.0, v62
	v_log_f32_e32 v62, v62
	v_add_f32_e32 v98, 1.0, v98
	v_rcp_f32_e32 v98, v98
	v_fmac_f32_e32 v63, 0x3f317218, v62
	v_mul_f32_e64 v62, v63, -v99
	ds_bpermute_b32 v242, v242, v62
	s_waitcnt lgkmcnt(0)
	v_fma_f32 v63, v63, -v99, v242
	v_cndmask_b32_e64 v62, v63, v62, s[42:43]
	v_add_u32_e32 v63, -2, v228
	v_cmp_lt_i32_e32 vcc, v63, v233
	s_nop 1
	v_cndmask_b32_e32 v63, v63, v228, vcc
	v_lshlrev_b32_e32 v63, 2, v63
	ds_bpermute_b32 v63, v63, v62
	s_waitcnt lgkmcnt(0)
	v_add_f32_e32 v63, v62, v63
	v_cndmask_b32_e64 v62, v63, v62, s[48:49]
	v_add_u32_e32 v63, -4, v228
	v_cmp_lt_i32_e32 vcc, v63, v233
	v_readlane_b32 s48, v255, 23
	v_readlane_b32 s49, v255, 24
	v_cndmask_b32_e32 v63, v63, v228, vcc
	v_lshlrev_b32_e32 v63, 2, v63
	ds_bpermute_b32 v63, v63, v62
	s_waitcnt lgkmcnt(0)
	v_add_f32_e32 v63, v62, v63
	v_cndmask_b32_e64 v62, v63, v62, s[48:49]
	v_add_u32_e32 v63, -8, v228
	v_cmp_lt_i32_e32 vcc, v63, v233
	v_readlane_b32 s48, v255, 25
	v_readlane_b32 s49, v255, 26
	v_cndmask_b32_e32 v63, v63, v228, vcc
	v_lshlrev_b32_e32 v63, 2, v63
	ds_bpermute_b32 v63, v63, v62
	s_waitcnt lgkmcnt(0)
	v_add_f32_e32 v63, v62, v63
	v_cndmask_b32_e64 v62, v63, v62, s[48:49]
	v_add_u32_e32 v63, -16, v228
	v_cmp_lt_i32_e32 vcc, v63, v233
	v_readlane_b32 s48, v255, 27
	v_readlane_b32 s49, v255, 28
	v_cndmask_b32_e32 v63, v63, v228, vcc
	v_lshlrev_b32_e32 v63, 2, v63
	ds_bpermute_b32 v63, v63, v62
	s_waitcnt lgkmcnt(0)
	v_add_f32_e32 v63, v62, v63
	v_cndmask_b32_e64 v62, v63, v62, s[48:49]
	v_subrev_u32_e32 v63, 32, v228
	v_cmp_lt_i32_e32 vcc, v63, v233
	s_nop 1
	v_cndmask_b32_e32 v63, v63, v228, vcc
	v_lshlrev_b32_e32 v63, 2, v63
	ds_bpermute_b32 v63, v63, v62
	s_waitcnt lgkmcnt(0)
	v_add_f32_e32 v63, v62, v63
	v_cndmask_b32_e64 v63, v63, v62, s[52:53]
	v_bfrev_b32_e32 v62, 0.5
	v_lshl_or_b32 v62, v228, 2, v62
	ds_bpermute_b32 v62, v62, v63
	ds_write_b32 v73, v98
	ds_write_b32 v101, v63
	s_and_saveexec_b64 s[62:63], s[42:43]
	s_cbranch_execz .LBB0_720
	s_lshl_b64 s[48:49], s[76:77], 2
	v_readlane_b32 s50, v255, 29
	s_waitcnt lgkmcnt(2)
	v_mul_f32_e32 v63, 0x3fb8aa3b, v62
	s_add_u32 s48, s50, s48
	v_readlane_b32 s50, v255, 30
	v_exp_f32_e32 v98, v63
	s_addc_u32 s49, s50, s49
	v_readlane_b32 s50, v255, 1
	s_nop 1
	v_mov_b32_e32 v63, s50
	ds_write_b32 v63, v62
	v_mov_b64_e32 v[62:63], s[48:49]
	flat_store_dword v[62:63], v98

; #define GAS __attribute__((address_space(1)))
; #define LAS __attribute__((address_space(3)))
; DI float bflo(unsigned w) { return __uint_as_float(w << 16); }
; DI float bfhi(unsigned w) { return __uint_as_float(w & 0xffff0000u); }
;     ...
;         const int t2 = tid >> 3, c02 = 16 * (tid & 7);
;         const int pcol2 = PC_V + h * 128 + c02, wch2 = 1536 + h * 128 + c02;
;         float av[16];
; #pragma unroll
;         for (int c = 0; c < 16; ++c) av[c] = 0.f;
;         v4u xv[4][2];
; #pragma unroll
;         for (int j = 0; j < 4; ++j) {
;             const int tt = t0 + t2 - 3 + j;
;             if (tt >= 0) { const bf16* src = P + ((size_t)b * SEQ + tt) * NP + pcol2; xv[j][0] = *(const GAS v4u*)src; xv[j][1] = *(const GAS v4u*)(src + 8); }
;         }
; #pragma unroll
;         for (int j = 0; j < 4; ++j) {
;             const int tt = t0 + t2 - 3 + j;
;             if (tt >= 0) {
;                 const LAS float* wp = (const LAS float*)(L + gp::CW) + j * 384 + 256 + c02;
; #pragma unroll
;                 for (int q4 = 0; q4 < 2; ++q4) {
;                     const v4u x = xv[j][q4]; const f32x4 w0 = *(const LAS f32x4*)(wp + 8 * q4), w1 = *(const LAS f32x4*)(wp + 8 * q4 + 4);
;                     av[8 * q4 + 0] += bflo(x.x) * w0.x; av[8 * q4 + 1] += bfhi(x.x) * w0.y; av[8 * q4 + 2] += bflo(x.y) * w0.z; av[8 * q4 + 3] += bfhi(x.y) * w0.w;
;                     av[8 * q4 + 4] += bflo(x.z) * w1.x; av[8 * q4 + 5] += bfhi(x.z) * w1.y; av[8 * q4 + 6] += bflo(x.w) * w1.z; av[8 * q4 + 7] += bfhi(x.w) * w1.w;
;                 }
;             }
;         }
.LBB0_721:
	s_and_saveexec_b64 s[100:101], s[40:41]
	s_waitcnt vmcnt(24)
	ds_write_b128 v192, v[238:241]
	s_mov_b64 exec, s[100:101]
	v_readlane_b32 s48, v255, 1
	s_waitcnt lgkmcnt(0)
	s_waitcnt lgkmcnt(0)
	s_barrier
	v_mov_b32_e32 v62, s48
	ds_read_b32 v75, v62
	s_lshl_b32 s48, s60, 7
	v_add_u32_e32 v96, s48, v131
	v_add_u32_e32 v32, s2, v132
	v_mov_b32_e32 v33, v97
	v_mov_b32_e32 v35, v97
	v_mov_b32_e32 v95, v97
	v_mov_b32_e32 v93, v97
	v_cmp_lt_i32_e64 s[70:71], -1, v32
	v_add_u32_e32 v34, 1, v32
	v_cmp_lt_i32_e64 s[68:69], -2, v32
	v_add_u32_e32 v94, 2, v32
	v_cmp_lt_i32_e64 s[66:67], -3, v32
	v_add_u32_e32 v92, s2, v130
	v_cmp_lt_i32_e32 vcc, -1, v92
	v_mov_b32_e32 v96, v97
	v_cmp_lt_i32_e64 s[64:65], 2, v92
	v_mov_b64_e32 v[76:77], v[96:97]
	v_mov_b64_e32 v[78:79], v[96:97]
	v_mov_b64_e32 v[80:81], v[96:97]
	v_mov_b64_e32 v[82:83], v[96:97]
	v_mov_b64_e32 v[84:85], v[96:97]
	v_mov_b64_e32 v[86:87], v[96:97]
	v_mov_b64_e32 v[88:89], v[96:97]
	v_mov_b64_e32 v[90:91], v[96:97]
	s_and_saveexec_b64 s[60:61], s[64:65]
	s_cbranch_execz .LBB0_733
	ds_read_b128 v[36:39], v133
	ds_read_b128 v[40:43], v133 offset:16
	ds_read_b128 v[44:47], v133 offset:32
	ds_read_b128 v[48:51], v133 offset:48
	s_waitcnt vmcnt(0)
	v_and_b32_e32 v53, 0xffff0000, v28
	v_lshlrev_b32_e32 v52, 16, v28
	s_waitcnt lgkmcnt(3)
	v_pk_fma_f32 v[90:91], v[36:37], v[52:53], 0 op_sel_hi:[1,1,0]
	v_and_b32_e32 v37, 0xffff0000, v29
	v_lshlrev_b32_e32 v36, 16, v29
	v_and_b32_e32 v29, 0xffff0000, v30
	v_lshlrev_b32_e32 v28, 16, v30
	s_waitcnt lgkmcnt(2)
	v_pk_fma_f32 v[86:87], v[40:41], v[28:29], 0 op_sel_hi:[1,1,0]
	v_and_b32_e32 v29, 0xffff0000, v31
	v_lshlrev_b32_e32 v28, 16, v31
	v_pk_fma_f32 v[84:85], v[42:43], v[28:29], 0 op_sel_hi:[1,1,0]
	v_and_b32_e32 v29, 0xffff0000, v24
	v_lshlrev_b32_e32 v28, 16, v24
	s_waitcnt lgkmcnt(1)
	v_pk_fma_f32 v[82:83], v[44:45], v[28:29], 0 op_sel_hi:[1,1,0]
	v_and_b32_e32 v29, 0xffff0000, v25
	v_lshlrev_b32_e32 v28, 16, v25
	v_and_b32_e32 v25, 0xffff0000, v26
	v_lshlrev_b32_e32 v24, 16, v26
	s_waitcnt lgkmcnt(0)
	v_pk_fma_f32 v[78:79], v[48:49], v[24:25], 0 op_sel_hi:[1,1,0]
	v_and_b32_e32 v25, 0xffff0000, v27
	v_lshlrev_b32_e32 v24, 16, v27
	v_pk_fma_f32 v[88:89], v[38:39], v[36:37], 0 op_sel_hi:[1,1,0]
	v_pk_fma_f32 v[80:81], v[46:47], v[28:29], 0 op_sel_hi:[1,1,0]
	v_pk_fma_f32 v[76:77], v[50:51], v[24:25], 0 op_sel_hi:[1,1,0]
	s_or_b64 exec, exec, s[60:61]
	v_cmp_lt_i32_e64 s[62:63], 1, v92
	s_and_saveexec_b64 s[60:61], s[62:63]
	s_cbranch_execnz .LBB0_734
